# output-projection epilogues of both layers: residual loads of row groups 1-3 issued early into dead fragment registers (one exposed round trip instead of four), on the v25 base
# baseline (speedup 1.0000x reference)
.LBB0_740:
	s_ashr_i32 s53, s52, 31
	s_ashr_i32 s55, s54, 31
	s_lshl_b64 s[58:59], s[52:53], 18
	s_lshl_b64 s[60:61], s[54:55], 8
	s_mul_i32 s31, s52, 0x2c0000
	v_mov_b32_e32 v132, v164
	s_movk_i32 s4, 0x1600
	s_mul_hi_i32 s12, s52, 0x2c0000
	s_add_u32 s31, s19, s31
	s_addc_u32 s12, s25, s12
	v_mul_lo_u32 v26, v132, s4
	s_lshl_b64 s[72:73], s[54:55], 9
	v_or_b32_e32 v26, v26, v166
	s_add_u32 s72, s31, s72
	v_lshlrev_b32_e32 v26, 1, v26
	s_addc_u32 s73, s12, s73
	s_lshl_b64 s[52:53], s[52:53], 14
	v_readlane_b32 s4, v251, 21
	v_lshl_add_u64 v[162:163], s[72:73], 0, v[26:27]
	s_add_u32 s12, s4, s52
	v_readlane_b32 s4, v251, 22
	v_add_co_u32_e32 v180, vcc, s6, v162
	s_addc_u32 s31, s4, s53
	s_mov_b64 s[4:5], 0x2400
	v_addc_co_u32_e32 v181, vcc, 0, v163, vcc
	v_lshl_add_u64 v[158:159], v[162:163], 0, s[4:5]
	global_load_dwordx4 v[176:179], v[180:181], off offset:1024
	global_load_dwordx4 v[140:143], v[158:159], off offset:256
	s_mov_b32 s4, 0x2e000
	v_lshl_or_b32 v160, v132, 10, v166
	v_lshlrev_b32_e32 v26, 6, v132
	v_add_co_u32_e32 v132, vcc, s4, v162
	s_lshl_b32 s52, s54, 2
	s_nop 0
	v_addc_co_u32_e32 v133, vcc, 0, v163, vcc
	global_load_dwordx4 v[136:139], v[132:133], off offset:1024
	s_nop 0
	global_load_dwordx4 v[132:135], v[132:133], off offset:1280
	s_mov_b64 s[98:99], 0x58000
	v_lshl_add_u64 v[248:249], v[158:159], 0, s[98:99]
	global_load_dwordx4 v[190:193], v[248:249], off
	global_load_dwordx4 v[194:197], v[248:249], off offset:256
	s_mov_b64 s[98:99], 0x84000
	v_lshl_add_u64 v[248:249], v[158:159], 0, s[98:99]
	global_load_dwordx4 v[198:201], v[248:249], off
	global_load_dwordx4 v[202:205], v[248:249], off offset:256
	s_mov_b64 s[98:99], 0x160000
	v_lshl_add_u64 v[248:249], v[158:159], 0, s[98:99]
	global_load_dwordx4 v[206:209], v[248:249], off
	global_load_dwordx4 v[210:213], v[248:249], off offset:256
	s_mov_b64 s[98:99], 0x18c000
	v_lshl_add_u64 v[248:249], v[158:159], 0, s[98:99]
	global_load_dwordx4 v[214:217], v[248:249], off
	global_load_dwordx4 v[218:221], v[248:249], off offset:256
	s_ashr_i32 s53, s52, 31
	s_lshl_b64 s[52:53], s[52:53], 2
	s_add_u32 s12, s12, s52
	s_addc_u32 s31, s31, s53
	s_add_u32 s52, s12, s68
	s_addc_u32 s53, s31, 0
	v_readlane_b32 s4, v251, 31
	s_add_u32 s12, s4, s58
	v_readlane_b32 s4, v251, 32
	s_addc_u32 s31, s4, s59
	v_lshl_add_u64 v[156:157], s[52:53], 0, v[26:27]
	s_add_u32 s52, s12, s60
	s_addc_u32 s53, s31, s61
	s_waitcnt vmcnt(8)
	v_lshlrev_b32_e32 v182, 16, v176
	v_and_b32_e32 v183, 0xffff0000, v176
	v_lshlrev_b32_e32 v176, 16, v177
	v_and_b32_e32 v177, 0xffff0000, v177
	v_pk_add_f32 v[184:185], v[4:5], v[176:177]
	v_lshlrev_b32_e32 v176, 16, v178
	v_and_b32_e32 v177, 0xffff0000, v178
	v_pk_add_f32 v[182:183], v[2:3], v[182:183]
	v_lshlrev_b32_e32 v178, 16, v179
	v_and_b32_e32 v179, 0xffff0000, v179
	v_pk_add_f32 v[188:189], v[6:7], v[176:177]
	v_cvt_pk_bf16_f32 v176, v182, v183
	v_cvt_pk_bf16_f32 v177, v184, v185
	v_pk_add_f32 v[186:187], v[8:9], v[178:179]
	v_cvt_pk_bf16_f32 v178, v188, v189
	v_mul_f32_e32 v26, v183, v183
	v_cvt_pk_bf16_f32 v179, v186, v187
	global_store_dwordx4 v[180:181], v[176:179], off offset:1024
	v_fmac_f32_e32 v26, v182, v182
	v_mul_f32_e32 v161, v185, v185
	v_mov_b32_e32 v176, v27
	v_mov_b32_e32 v177, v27
	v_cvt_pk_fp8_f32 v176, v182, v183
	v_cvt_pk_fp8_f32 v177, v188, v189
	v_fmac_f32_e32 v161, v184, v184
	v_add_f32_e32 v26, v26, v161
	v_cvt_pk_fp8_f32 v176, v184, v185 op_sel:[0,0,1]
	v_cvt_pk_fp8_f32 v177, v186, v187 op_sel:[0,0,1]
	v_mul_f32_e32 v161, v189, v189
	v_fmac_f32_e32 v161, v188, v188
	v_add_f32_e32 v26, v161, v26
	global_store_dwordx2 v160, v[176:177], s[52:53]
	v_lshlrev_b32_e32 v176, 16, v140
	v_and_b32_e32 v177, 0xffff0000, v140
	v_lshlrev_b32_e32 v140, 16, v141
	v_and_b32_e32 v141, 0xffff0000, v141
	v_pk_add_f32 v[178:179], v[38:39], v[140:141]
	v_pk_add_f32 v[176:177], v[36:37], v[176:177]
	v_lshlrev_b32_e32 v140, 16, v142
	v_and_b32_e32 v141, 0xffff0000, v142
	v_pk_add_f32 v[182:183], v[40:41], v[140:141]
	v_mul_f32_e32 v140, v177, v177
	v_mul_f32_e32 v141, v179, v179
	v_fmac_f32_e32 v140, v176, v176
	v_fmac_f32_e32 v141, v178, v178
	v_lshlrev_b32_e32 v142, 16, v143
	v_and_b32_e32 v143, 0xffff0000, v143
	v_add_f32_e32 v140, v140, v141
	v_mul_f32_e32 v141, v183, v183
	v_pk_add_f32 v[180:181], v[42:43], v[142:143]
	v_fmac_f32_e32 v141, v182, v182
	v_mul_f32_e32 v161, v187, v187
	v_add_f32_e32 v140, v141, v140
	v_mul_f32_e32 v141, v181, v181
	v_fmac_f32_e32 v161, v186, v186
	v_fmac_f32_e32 v141, v180, v180
	v_add_f32_e32 v26, v161, v26
	v_add_f32_e32 v140, v141, v140
	v_add_f32_e32 v161, v26, v140
	v_cvt_pk_bf16_f32 v140, v176, v177
	v_cvt_pk_bf16_f32 v141, v178, v179
	v_cvt_pk_bf16_f32 v142, v182, v183
	v_cvt_pk_bf16_f32 v143, v180, v181
	global_store_dwordx4 v[158:159], v[140:143], off offset:256
	v_xor_b32_e32 v26, 16, v224
	s_nop 0
	v_mov_b32_e32 v140, v27
	v_mov_b32_e32 v141, v27
	v_cvt_pk_fp8_f32 v140, v176, v177
	v_cvt_pk_fp8_f32 v141, v182, v183
	v_xor_b32_e32 v142, 32, v224
	v_cvt_pk_fp8_f32 v140, v178, v179 op_sel:[0,0,1]
	v_cvt_pk_fp8_f32 v141, v180, v181 op_sel:[0,0,1]
	global_store_dwordx2 v160, v[140:141], s[52:53] offset:128
	v_and_b32_e32 v140, 64, v224
	v_add_u32_e32 v141, 64, v140
	v_cmp_lt_i32_e32 vcc, v26, v141
	s_nop 1
	v_cndmask_b32_e32 v26, v224, v26, vcc
	v_lshlrev_b32_e32 v26, 2, v26
	ds_bpermute_b32 v140, v26, v161
	v_cmp_lt_i32_e32 vcc, v142, v141
	s_waitcnt lgkmcnt(0)
	v_add_f32_e32 v140, v161, v140
	v_cndmask_b32_e32 v141, v224, v142, vcc
	v_lshlrev_b32_e32 v176, 2, v141
	ds_bpermute_b32 v141, v176, v140
	s_and_saveexec_b64 s[54:55], s[0:1]
	v_readlane_b32 s84, v250, 16
	v_readlane_b32 s85, v250, 17
	s_mov_b32 s81, 0x16000
	s_mov_b64 s[86:87], 0xc00
	s_cbranch_execz .LBB0_742
	s_waitcnt lgkmcnt(0)
	v_add_f32_e32 v140, v140, v141
	global_store_dword v[156:157], v140, off

.LBB0_744:
	s_or_b64 exec, exec, s[52:53]
	v_add_co_u32_e32 v182, vcc, 0x58000, v158
	s_mov_b32 s4, 0x8000
	s_nop 0
	v_addc_co_u32_e32 v183, vcc, 0, v159, vcc
	s_waitcnt vmcnt(12)
	v_mov_b64_e32 v[160:161], v[190:191]
	v_mov_b64_e32 v[162:163], v[192:193]
	v_mov_b64_e32 v[178:179], v[194:195]
	v_mov_b64_e32 v[180:181], v[196:197]
	v_mov_b64_e32 v[136:137], v[198:199]
	v_mov_b64_e32 v[138:139], v[200:201]
	v_mov_b64_e32 v[132:133], v[202:203]
	v_mov_b64_e32 v[134:135], v[204:205]
	s_mov_b64 s[98:99], 0x1b8000
	v_lshl_add_u64 v[248:249], v[158:159], 0, s[98:99]
	global_load_dwordx4 v[190:193], v[248:249], off
	global_load_dwordx4 v[194:197], v[248:249], off offset:256
	s_mov_b64 s[98:99], 0x1e4000
	v_lshl_add_u64 v[248:249], v[158:159], 0, s[98:99]
	global_load_dwordx4 v[198:201], v[248:249], off
	global_load_dwordx4 v[202:205], v[248:249], off offset:256
	v_lshlrev_b32_e32 v142, 16, v160
	s_waitcnt lgkmcnt(0)
	v_and_b32_e32 v143, 0xffff0000, v160
	v_lshlrev_b32_e32 v160, 16, v161
	v_and_b32_e32 v161, 0xffff0000, v161
	v_pk_add_f32 v[184:185], v[20:21], v[160:161]
	v_pk_add_f32 v[142:143], v[18:19], v[142:143]
	v_lshlrev_b32_e32 v160, 16, v162
	v_and_b32_e32 v161, 0xffff0000, v162
	v_pk_add_f32 v[188:189], v[22:23], v[160:161]
	v_mul_f32_e32 v160, v143, v143
	v_mul_f32_e32 v161, v185, v185
	v_fmac_f32_e32 v160, v142, v142
	v_fmac_f32_e32 v161, v184, v184
	v_lshlrev_b32_e32 v162, 16, v163
	v_and_b32_e32 v163, 0xffff0000, v163
	v_add_f32_e32 v160, v160, v161
	v_mul_f32_e32 v161, v189, v189
	v_pk_add_f32 v[186:187], v[24:25], v[162:163]
	v_fmac_f32_e32 v161, v188, v188
	v_add_f32_e32 v160, v161, v160
	v_mul_f32_e32 v161, v187, v187
	v_fmac_f32_e32 v161, v186, v186
	v_add_f32_e32 v177, v161, v160
	v_cvt_pk_bf16_f32 v160, v142, v143
	v_cvt_pk_bf16_f32 v161, v184, v185
	v_cvt_pk_bf16_f32 v162, v188, v189
	v_cvt_pk_bf16_f32 v163, v186, v187
	global_store_dwordx4 v[182:183], v[160:163], off
	s_nop 1
	v_mov_b32_e32 v160, v27
	v_mov_b32_e32 v161, v27
	v_cvt_pk_fp8_f32 v160, v142, v143
	v_cvt_pk_fp8_f32 v161, v188, v189
	v_add_co_u32_e32 v142, vcc, s4, v140
	v_cvt_pk_fp8_f32 v160, v184, v185 op_sel:[0,0,1]
	v_cvt_pk_fp8_f32 v161, v186, v187 op_sel:[0,0,1]
	v_addc_co_u32_e32 v143, vcc, 0, v141, vcc
	v_lshlrev_b32_e32 v162, 16, v179
	global_store_dwordx2 v[142:143], v[160:161], off
	v_lshlrev_b32_e32 v160, 16, v178
	v_and_b32_e32 v161, 0xffff0000, v178
	v_and_b32_e32 v163, 0xffff0000, v179
	v_pk_add_f32 v[184:185], v[54:55], v[162:163]
	v_pk_add_f32 v[186:187], v[52:53], v[160:161]
	v_lshlrev_b32_e32 v162, 16, v180
	v_and_b32_e32 v163, 0xffff0000, v180
	v_mul_f32_e32 v178, v187, v187
	v_mul_f32_e32 v179, v185, v185
	v_pk_add_f32 v[162:163], v[56:57], v[162:163]
	v_fmac_f32_e32 v178, v186, v186
	v_fmac_f32_e32 v179, v184, v184
	v_lshlrev_b32_e32 v160, 16, v181
	v_and_b32_e32 v161, 0xffff0000, v181
	v_add_f32_e32 v178, v178, v179
	v_mul_f32_e32 v179, v163, v163
	v_pk_add_f32 v[160:161], v[58:59], v[160:161]
	v_fmac_f32_e32 v179, v162, v162
	v_add_f32_e32 v178, v179, v178
	v_mul_f32_e32 v179, v161, v161
	v_fmac_f32_e32 v179, v160, v160
	v_add_f32_e32 v178, v179, v178
	v_add_f32_e32 v177, v177, v178
	v_cvt_pk_bf16_f32 v178, v186, v187
	v_cvt_pk_bf16_f32 v179, v184, v185
	v_cvt_pk_bf16_f32 v180, v162, v163
	v_cvt_pk_bf16_f32 v181, v160, v161
	global_store_dwordx4 v[182:183], v[178:181], off offset:256
	s_nop 1
	v_mov_b32_e32 v178, v27
	v_mov_b32_e32 v179, v27
	v_cvt_pk_fp8_f32 v178, v186, v187
	v_cvt_pk_fp8_f32 v179, v162, v163
	v_cvt_pk_fp8_f32 v178, v184, v185 op_sel:[0,0,1]
	v_cvt_pk_fp8_f32 v179, v160, v161 op_sel:[0,0,1]
	global_store_dwordx2 v[142:143], v[178:179], off offset:128
	ds_bpermute_b32 v142, v26, v177
	s_waitcnt lgkmcnt(0)
	v_add_f32_e32 v142, v177, v142
	ds_bpermute_b32 v143, v176, v142
	s_and_saveexec_b64 s[52:53], s[0:1]
	s_cbranch_execz .LBB0_746
	s_waitcnt lgkmcnt(0)
	v_add_f32_e32 v142, v142, v143
	global_store_dword v[156:157], v142, off offset:2048
.LBB0_746:
	s_or_b64 exec, exec, s[52:53]
	v_lshlrev_b32_e32 v162, 16, v136
	v_and_b32_e32 v163, 0xffff0000, v136
	v_lshlrev_b32_e32 v136, 16, v137
	v_and_b32_e32 v137, 0xffff0000, v137
	v_pk_add_f32 v[178:179], v[30:31], v[136:137]
	v_pk_add_f32 v[162:163], v[28:29], v[162:163]
	v_lshlrev_b32_e32 v136, 16, v138
	v_and_b32_e32 v137, 0xffff0000, v138
	v_pk_add_f32 v[182:183], v[32:33], v[136:137]
	v_mul_f32_e32 v136, v163, v163
	v_mul_f32_e32 v137, v179, v179
	v_fmac_f32_e32 v136, v162, v162
	v_fmac_f32_e32 v137, v178, v178
	v_lshlrev_b32_e32 v138, 16, v139
	v_and_b32_e32 v139, 0xffff0000, v139
	v_add_f32_e32 v136, v136, v137
	v_mul_f32_e32 v137, v183, v183
	v_pk_add_f32 v[180:181], v[34:35], v[138:139]
	v_fmac_f32_e32 v137, v182, v182
	v_add_f32_e32 v136, v137, v136
	v_mul_f32_e32 v137, v181, v181
	s_mov_b64 s[52:53], 0x84000
	v_fmac_f32_e32 v137, v180, v180
	s_waitcnt lgkmcnt(0)
	v_lshl_add_u64 v[142:143], v[158:159], 0, s[52:53]
	v_add_f32_e32 v177, v137, v136
	v_cvt_pk_bf16_f32 v136, v162, v163
	v_cvt_pk_bf16_f32 v137, v178, v179
	v_cvt_pk_bf16_f32 v138, v182, v183
	v_cvt_pk_bf16_f32 v139, v180, v181
	global_store_dwordx4 v[142:143], v[136:139], off
	s_mov_b32 s12, 0xc000
	s_mov_b64 s[52:53], 0x84100
	v_mov_b32_e32 v136, v27
	v_mov_b32_e32 v137, v27
	v_cvt_pk_fp8_f32 v136, v162, v163
	v_cvt_pk_fp8_f32 v137, v182, v183
	v_add_co_u32_e32 v138, vcc, s12, v140
	v_cvt_pk_fp8_f32 v136, v178, v179 op_sel:[0,0,1]
	v_cvt_pk_fp8_f32 v137, v180, v181 op_sel:[0,0,1]
	v_addc_co_u32_e32 v139, vcc, 0, v141, vcc
	v_lshl_add_u64 v[160:161], v[158:159], 0, s[52:53]
	global_store_dwordx2 v[138:139], v[136:137], off
	v_lshlrev_b32_e32 v136, 16, v132
	v_and_b32_e32 v137, 0xffff0000, v132
	v_lshlrev_b32_e32 v132, 16, v133
	v_and_b32_e32 v133, 0xffff0000, v133
	v_pk_add_f32 v[142:143], v[62:63], v[132:133]
	v_pk_add_f32 v[136:137], v[60:61], v[136:137]
	v_lshlrev_b32_e32 v132, 16, v134
	v_and_b32_e32 v133, 0xffff0000, v134
	v_pk_add_f32 v[178:179], v[64:65], v[132:133]
	v_mul_f32_e32 v132, v137, v137
	v_mul_f32_e32 v133, v143, v143
	v_fmac_f32_e32 v132, v136, v136
	v_fmac_f32_e32 v133, v142, v142
	v_lshlrev_b32_e32 v134, 16, v135
	v_and_b32_e32 v135, 0xffff0000, v135
	v_add_f32_e32 v132, v132, v133
	v_mul_f32_e32 v133, v179, v179
	v_pk_add_f32 v[162:163], v[66:67], v[134:135]
	v_fmac_f32_e32 v133, v178, v178
	v_add_f32_e32 v132, v133, v132
	v_mul_f32_e32 v133, v163, v163
	v_fmac_f32_e32 v133, v162, v162
	v_add_f32_e32 v132, v133, v132
	v_add_f32_e32 v177, v177, v132
	v_cvt_pk_bf16_f32 v132, v136, v137
	v_cvt_pk_bf16_f32 v133, v142, v143
	v_cvt_pk_bf16_f32 v134, v178, v179
	v_cvt_pk_bf16_f32 v135, v162, v163
	global_store_dwordx4 v[160:161], v[132:135], off
	s_nop 1
	v_mov_b32_e32 v132, v27
	v_mov_b32_e32 v133, v27
	v_cvt_pk_fp8_f32 v132, v136, v137
	v_cvt_pk_fp8_f32 v133, v178, v179
	v_cvt_pk_fp8_f32 v132, v142, v143 op_sel:[0,0,1]
	v_cvt_pk_fp8_f32 v133, v162, v163 op_sel:[0,0,1]
	global_store_dwordx2 v[138:139], v[132:133], off offset:128
	ds_bpermute_b32 v132, v26, v177
	s_waitcnt lgkmcnt(0)
	v_add_f32_e32 v132, v177, v132
	ds_bpermute_b32 v133, v176, v132
	s_and_saveexec_b64 s[52:53], s[0:1]
	s_cbranch_execz .LBB0_748
	s_waitcnt lgkmcnt(0)
	v_add_f32_e32 v132, v132, v133
	global_store_dword v[156:157], v132, off offset:3072
.LBB0_748:
	s_or_b64 exec, exec, s[52:53]
	v_add_co_u32_e32 v182, vcc, 0x160000, v158
	s_mov_b32 s4, 0x20000
	s_nop 0
	v_addc_co_u32_e32 v183, vcc, 0, v159, vcc
	s_waitcnt vmcnt(20)
	v_mov_b64_e32 v[160:161], v[206:207]
	v_mov_b64_e32 v[162:163], v[208:209]
	v_mov_b64_e32 v[178:179], v[210:211]
	v_mov_b64_e32 v[180:181], v[212:213]
	v_mov_b64_e32 v[136:137], v[214:215]
	v_mov_b64_e32 v[138:139], v[216:217]
	v_mov_b64_e32 v[132:133], v[218:219]
	v_mov_b64_e32 v[134:135], v[220:221]
	v_lshlrev_b32_e32 v142, 16, v160
	s_waitcnt lgkmcnt(0)
	v_and_b32_e32 v143, 0xffff0000, v160
	v_lshlrev_b32_e32 v160, 16, v161
	v_and_b32_e32 v161, 0xffff0000, v161
	v_pk_add_f32 v[184:185], v[70:71], v[160:161]
	v_pk_add_f32 v[142:143], v[68:69], v[142:143]
	v_lshlrev_b32_e32 v160, 16, v162
	v_and_b32_e32 v161, 0xffff0000, v162
	v_pk_add_f32 v[188:189], v[72:73], v[160:161]
	v_mul_f32_e32 v160, v143, v143
	v_mul_f32_e32 v161, v185, v185
	v_fmac_f32_e32 v160, v142, v142
	v_fmac_f32_e32 v161, v184, v184
	v_lshlrev_b32_e32 v162, 16, v163
	v_and_b32_e32 v163, 0xffff0000, v163
	v_add_f32_e32 v160, v160, v161
	v_mul_f32_e32 v161, v189, v189
	v_pk_add_f32 v[186:187], v[74:75], v[162:163]
	v_fmac_f32_e32 v161, v188, v188
	v_add_f32_e32 v160, v161, v160
	v_mul_f32_e32 v161, v187, v187
	v_fmac_f32_e32 v161, v186, v186
	v_add_f32_e32 v177, v161, v160
	v_cvt_pk_bf16_f32 v160, v142, v143
	v_cvt_pk_bf16_f32 v161, v184, v185
	v_cvt_pk_bf16_f32 v162, v188, v189
	v_cvt_pk_bf16_f32 v163, v186, v187
	global_store_dwordx4 v[182:183], v[160:163], off
	s_nop 1
	v_mov_b32_e32 v160, v27
	v_mov_b32_e32 v161, v27
	v_cvt_pk_fp8_f32 v160, v142, v143
	v_cvt_pk_fp8_f32 v161, v188, v189
	v_add_co_u32_e32 v142, vcc, s4, v140
	v_cvt_pk_fp8_f32 v160, v184, v185 op_sel:[0,0,1]
	v_cvt_pk_fp8_f32 v161, v186, v187 op_sel:[0,0,1]
	v_addc_co_u32_e32 v143, vcc, 0, v141, vcc
	v_lshlrev_b32_e32 v162, 16, v179
	global_store_dwordx2 v[142:143], v[160:161], off
	v_lshlrev_b32_e32 v160, 16, v178
	v_and_b32_e32 v161, 0xffff0000, v178
	v_and_b32_e32 v163, 0xffff0000, v179
	v_pk_add_f32 v[184:185], v[102:103], v[162:163]
	v_pk_add_f32 v[186:187], v[100:101], v[160:161]
	v_lshlrev_b32_e32 v162, 16, v180
	v_and_b32_e32 v163, 0xffff0000, v180
	v_mul_f32_e32 v178, v187, v187
	v_mul_f32_e32 v179, v185, v185
	v_pk_add_f32 v[162:163], v[104:105], v[162:163]
	v_fmac_f32_e32 v178, v186, v186
	v_fmac_f32_e32 v179, v184, v184
	v_lshlrev_b32_e32 v160, 16, v181
	v_and_b32_e32 v161, 0xffff0000, v181
	v_add_f32_e32 v178, v178, v179
	v_mul_f32_e32 v179, v163, v163
	v_pk_add_f32 v[160:161], v[106:107], v[160:161]
	v_fmac_f32_e32 v179, v162, v162
	v_add_f32_e32 v178, v179, v178
	v_mul_f32_e32 v179, v161, v161
	v_fmac_f32_e32 v179, v160, v160
	v_add_f32_e32 v178, v179, v178
	v_add_f32_e32 v177, v177, v178
	v_cvt_pk_bf16_f32 v178, v186, v187
	v_cvt_pk_bf16_f32 v179, v184, v185
	v_cvt_pk_bf16_f32 v180, v162, v163
	v_cvt_pk_bf16_f32 v181, v160, v161
	global_store_dwordx4 v[182:183], v[178:181], off offset:256
	s_nop 1
	v_mov_b32_e32 v178, v27
	v_mov_b32_e32 v179, v27
	v_cvt_pk_fp8_f32 v178, v186, v187
	v_cvt_pk_fp8_f32 v179, v162, v163
	v_cvt_pk_fp8_f32 v178, v184, v185 op_sel:[0,0,1]
	v_cvt_pk_fp8_f32 v179, v160, v161 op_sel:[0,0,1]
	global_store_dwordx2 v[142:143], v[178:179], off offset:128
	ds_bpermute_b32 v142, v26, v177
	s_waitcnt lgkmcnt(0)
	v_add_f32_e32 v142, v177, v142
	ds_bpermute_b32 v143, v176, v142
	s_and_saveexec_b64 s[52:53], s[0:1]
	s_cbranch_execz .LBB0_750
	s_waitcnt lgkmcnt(0)
	v_add_f32_e32 v160, v142, v143
	v_add_co_u32_e32 v142, vcc, 0x2000, v156
	s_nop 1
	v_addc_co_u32_e32 v143, vcc, 0, v157, vcc
	global_store_dword v[142:143], v160, off
.LBB0_750:
	s_or_b64 exec, exec, s[52:53]
	v_lshlrev_b32_e32 v162, 16, v136
	v_and_b32_e32 v163, 0xffff0000, v136
	v_lshlrev_b32_e32 v136, 16, v137
	v_and_b32_e32 v137, 0xffff0000, v137
	v_pk_add_f32 v[178:179], v[78:79], v[136:137]
	v_pk_add_f32 v[162:163], v[76:77], v[162:163]
	v_lshlrev_b32_e32 v136, 16, v138
	v_and_b32_e32 v137, 0xffff0000, v138
	v_pk_add_f32 v[182:183], v[80:81], v[136:137]
	v_mul_f32_e32 v136, v163, v163
	v_mul_f32_e32 v137, v179, v179
	v_fmac_f32_e32 v136, v162, v162
	v_fmac_f32_e32 v137, v178, v178
	v_lshlrev_b32_e32 v138, 16, v139
	v_and_b32_e32 v139, 0xffff0000, v139
	v_add_f32_e32 v136, v136, v137
	v_mul_f32_e32 v137, v183, v183
	v_pk_add_f32 v[180:181], v[82:83], v[138:139]
	v_fmac_f32_e32 v137, v182, v182
	v_add_f32_e32 v136, v137, v136
	v_mul_f32_e32 v137, v181, v181
	s_mov_b64 s[52:53], 0x18c000
	v_fmac_f32_e32 v137, v180, v180
	s_waitcnt lgkmcnt(0)
	v_lshl_add_u64 v[142:143], v[158:159], 0, s[52:53]
	v_add_f32_e32 v177, v137, v136
	v_cvt_pk_bf16_f32 v136, v162, v163
	v_cvt_pk_bf16_f32 v137, v178, v179
	v_cvt_pk_bf16_f32 v138, v182, v183
	v_cvt_pk_bf16_f32 v139, v180, v181
	global_store_dwordx4 v[142:143], v[136:139], off
	s_mov_b32 s4, 0x24000
	s_mov_b64 s[52:53], 0x18c100
	v_mov_b32_e32 v136, v27
	v_mov_b32_e32 v137, v27
	v_cvt_pk_fp8_f32 v136, v162, v163
	v_cvt_pk_fp8_f32 v137, v182, v183
	v_add_co_u32_e32 v138, vcc, s4, v140
	v_cvt_pk_fp8_f32 v136, v178, v179 op_sel:[0,0,1]
	v_cvt_pk_fp8_f32 v137, v180, v181 op_sel:[0,0,1]
	v_addc_co_u32_e32 v139, vcc, 0, v141, vcc
	v_lshl_add_u64 v[160:161], v[158:159], 0, s[52:53]
	global_store_dwordx2 v[138:139], v[136:137], off
	v_lshlrev_b32_e32 v136, 16, v132
	v_and_b32_e32 v137, 0xffff0000, v132
	v_lshlrev_b32_e32 v132, 16, v133
	v_and_b32_e32 v133, 0xffff0000, v133
	v_pk_add_f32 v[142:143], v[110:111], v[132:133]
	v_pk_add_f32 v[136:137], v[108:109], v[136:137]
	v_lshlrev_b32_e32 v132, 16, v134
	v_and_b32_e32 v133, 0xffff0000, v134
	v_pk_add_f32 v[178:179], v[112:113], v[132:133]
	v_mul_f32_e32 v132, v137, v137
	v_mul_f32_e32 v133, v143, v143
	v_fmac_f32_e32 v132, v136, v136
	v_fmac_f32_e32 v133, v142, v142
	v_lshlrev_b32_e32 v134, 16, v135
	v_and_b32_e32 v135, 0xffff0000, v135
	v_add_f32_e32 v132, v132, v133
	v_mul_f32_e32 v133, v179, v179
	v_pk_add_f32 v[162:163], v[114:115], v[134:135]
	v_fmac_f32_e32 v133, v178, v178
	v_add_f32_e32 v132, v133, v132
	v_mul_f32_e32 v133, v163, v163
	v_fmac_f32_e32 v133, v162, v162
	v_add_f32_e32 v132, v133, v132
	v_add_f32_e32 v177, v177, v132
	v_cvt_pk_bf16_f32 v132, v136, v137
	v_cvt_pk_bf16_f32 v133, v142, v143
	v_cvt_pk_bf16_f32 v134, v178, v179
	v_cvt_pk_bf16_f32 v135, v162, v163
	global_store_dwordx4 v[160:161], v[132:135], off
	s_nop 1
	v_mov_b32_e32 v132, v27
	v_mov_b32_e32 v133, v27
	v_cvt_pk_fp8_f32 v132, v136, v137
	v_cvt_pk_fp8_f32 v133, v178, v179
	v_cvt_pk_fp8_f32 v132, v142, v143 op_sel:[0,0,1]
	v_cvt_pk_fp8_f32 v133, v162, v163 op_sel:[0,0,1]
	global_store_dwordx2 v[138:139], v[132:133], off offset:128
	ds_bpermute_b32 v132, v26, v177
	s_waitcnt lgkmcnt(0)
	v_add_f32_e32 v132, v177, v132
	ds_bpermute_b32 v133, v176, v132
	s_and_saveexec_b64 s[52:53], s[0:1]
	s_cbranch_execz .LBB0_752
	s_waitcnt lgkmcnt(0)
	v_add_f32_e32 v134, v132, v133
	v_add_co_u32_e32 v132, vcc, 0x2000, v156
	s_nop 1
	v_addc_co_u32_e32 v133, vcc, 0, v157, vcc
	global_store_dword v[132:133], v134, off offset:1024
.LBB0_752:
	s_or_b64 exec, exec, s[52:53]
	v_add_co_u32_e32 v182, vcc, 0x1b8000, v158
	s_mov_b32 s4, 0x28000
	s_nop 0
	v_addc_co_u32_e32 v183, vcc, 0, v159, vcc
	s_waitcnt vmcnt(16)
	v_mov_b64_e32 v[160:161], v[190:191]
	v_mov_b64_e32 v[162:163], v[192:193]
	v_mov_b64_e32 v[178:179], v[194:195]
	v_mov_b64_e32 v[180:181], v[196:197]
	v_mov_b64_e32 v[136:137], v[198:199]
	v_mov_b64_e32 v[138:139], v[200:201]
	v_mov_b64_e32 v[132:133], v[202:203]
	v_mov_b64_e32 v[134:135], v[204:205]
	v_lshlrev_b32_e32 v142, 16, v160
	s_waitcnt lgkmcnt(0)
	v_and_b32_e32 v143, 0xffff0000, v160
	v_lshlrev_b32_e32 v160, 16, v161
	v_and_b32_e32 v161, 0xffff0000, v161
	v_pk_add_f32 v[184:185], v[86:87], v[160:161]
	v_pk_add_f32 v[142:143], v[84:85], v[142:143]
	v_lshlrev_b32_e32 v160, 16, v162
	v_and_b32_e32 v161, 0xffff0000, v162
	v_pk_add_f32 v[188:189], v[88:89], v[160:161]
	v_mul_f32_e32 v160, v143, v143
	v_mul_f32_e32 v161, v185, v185
	v_fmac_f32_e32 v160, v142, v142
	v_fmac_f32_e32 v161, v184, v184
	v_lshlrev_b32_e32 v162, 16, v163
	v_and_b32_e32 v163, 0xffff0000, v163
	v_add_f32_e32 v160, v160, v161
	v_mul_f32_e32 v161, v189, v189
	v_pk_add_f32 v[186:187], v[90:91], v[162:163]
	v_fmac_f32_e32 v161, v188, v188
	v_add_f32_e32 v160, v161, v160
	v_mul_f32_e32 v161, v187, v187
	v_fmac_f32_e32 v161, v186, v186
	v_add_f32_e32 v177, v161, v160
	v_cvt_pk_bf16_f32 v160, v142, v143
	v_cvt_pk_bf16_f32 v161, v184, v185
	v_cvt_pk_bf16_f32 v162, v188, v189
	v_cvt_pk_bf16_f32 v163, v186, v187
	global_store_dwordx4 v[182:183], v[160:163], off
	s_nop 1
	v_mov_b32_e32 v160, v27
	v_mov_b32_e32 v161, v27
	v_cvt_pk_fp8_f32 v160, v142, v143
	v_cvt_pk_fp8_f32 v161, v188, v189
	v_add_co_u32_e32 v142, vcc, s4, v140
	v_cvt_pk_fp8_f32 v160, v184, v185 op_sel:[0,0,1]
	v_cvt_pk_fp8_f32 v161, v186, v187 op_sel:[0,0,1]
	v_addc_co_u32_e32 v143, vcc, 0, v141, vcc
	v_lshlrev_b32_e32 v162, 16, v179
	global_store_dwordx2 v[142:143], v[160:161], off
	v_lshlrev_b32_e32 v160, 16, v178
	v_and_b32_e32 v161, 0xffff0000, v178
	v_and_b32_e32 v163, 0xffff0000, v179
	v_pk_add_f32 v[184:185], v[118:119], v[162:163]
	v_pk_add_f32 v[186:187], v[116:117], v[160:161]
	v_lshlrev_b32_e32 v162, 16, v180
	v_and_b32_e32 v163, 0xffff0000, v180
	v_mul_f32_e32 v178, v187, v187
	v_mul_f32_e32 v179, v185, v185
	v_pk_add_f32 v[162:163], v[120:121], v[162:163]
	v_fmac_f32_e32 v178, v186, v186
	v_fmac_f32_e32 v179, v184, v184
	v_lshlrev_b32_e32 v160, 16, v181
	v_and_b32_e32 v161, 0xffff0000, v181
	v_add_f32_e32 v178, v178, v179
	v_mul_f32_e32 v179, v163, v163
	v_pk_add_f32 v[160:161], v[122:123], v[160:161]
	v_fmac_f32_e32 v179, v162, v162
	v_add_f32_e32 v178, v179, v178
	v_mul_f32_e32 v179, v161, v161
	v_fmac_f32_e32 v179, v160, v160
	v_add_f32_e32 v178, v179, v178
	v_add_f32_e32 v177, v177, v178
	v_cvt_pk_bf16_f32 v178, v186, v187
	v_cvt_pk_bf16_f32 v179, v184, v185
	v_cvt_pk_bf16_f32 v180, v162, v163
	v_cvt_pk_bf16_f32 v181, v160, v161
	global_store_dwordx4 v[182:183], v[178:181], off offset:256
	s_nop 1
	v_mov_b32_e32 v178, v27
	v_mov_b32_e32 v179, v27
	v_cvt_pk_fp8_f32 v178, v186, v187
	v_cvt_pk_fp8_f32 v179, v162, v163
	v_cvt_pk_fp8_f32 v178, v184, v185 op_sel:[0,0,1]
	v_cvt_pk_fp8_f32 v179, v160, v161 op_sel:[0,0,1]
	global_store_dwordx2 v[142:143], v[178:179], off offset:128
	ds_bpermute_b32 v142, v26, v177
	s_waitcnt lgkmcnt(0)
	v_add_f32_e32 v142, v177, v142
	ds_bpermute_b32 v143, v176, v142
	s_and_saveexec_b64 s[52:53], s[0:1]
	s_cbranch_execz .LBB0_754
	s_waitcnt lgkmcnt(0)
	v_add_f32_e32 v160, v142, v143
	v_add_co_u32_e32 v142, vcc, 0x2000, v156
	s_nop 1
	v_addc_co_u32_e32 v143, vcc, 0, v157, vcc
	global_store_dword v[142:143], v160, off offset:2048
.LBB0_754:
	s_or_b64 exec, exec, s[52:53]
	v_lshlrev_b32_e32 v160, 16, v136
	v_and_b32_e32 v161, 0xffff0000, v136
	v_lshlrev_b32_e32 v136, 16, v137
	v_and_b32_e32 v137, 0xffff0000, v137
	v_pk_add_f32 v[162:163], v[94:95], v[136:137]
	v_pk_add_f32 v[160:161], v[92:93], v[160:161]
	v_lshlrev_b32_e32 v136, 16, v138
	v_and_b32_e32 v137, 0xffff0000, v138
	v_pk_add_f32 v[180:181], v[96:97], v[136:137]
	v_mul_f32_e32 v136, v161, v161
	v_mul_f32_e32 v137, v163, v163
	v_fmac_f32_e32 v136, v160, v160
	v_fmac_f32_e32 v137, v162, v162
	v_lshlrev_b32_e32 v138, 16, v139
	v_and_b32_e32 v139, 0xffff0000, v139
	v_add_f32_e32 v136, v136, v137
	v_mul_f32_e32 v137, v181, v181
	v_pk_add_f32 v[178:179], v[98:99], v[138:139]
	v_fmac_f32_e32 v137, v180, v180
	v_add_f32_e32 v136, v137, v136
	v_mul_f32_e32 v137, v179, v179
	s_mov_b64 s[52:53], 0x1e4000
	v_fmac_f32_e32 v137, v178, v178
	s_waitcnt lgkmcnt(0)
	v_lshl_add_u64 v[142:143], v[158:159], 0, s[52:53]
	v_add_f32_e32 v177, v137, v136
	v_cvt_pk_bf16_f32 v136, v160, v161
	v_cvt_pk_bf16_f32 v137, v162, v163
	v_cvt_pk_bf16_f32 v138, v180, v181
	v_cvt_pk_bf16_f32 v139, v178, v179
	global_store_dwordx4 v[142:143], v[136:139], off
	s_mov_b32 s4, 0x2c000
	s_mov_b64 s[52:53], 0x1e4100
	v_mov_b32_e32 v136, v27
	v_mov_b32_e32 v137, v27
	v_cvt_pk_fp8_f32 v136, v160, v161
	v_cvt_pk_fp8_f32 v137, v180, v181
	v_add_co_u32_e32 v138, vcc, s4, v140
	v_cvt_pk_fp8_f32 v136, v162, v163 op_sel:[0,0,1]
	v_cvt_pk_fp8_f32 v137, v178, v179 op_sel:[0,0,1]
	v_addc_co_u32_e32 v139, vcc, 0, v141, vcc
	v_lshl_add_u64 v[158:159], v[158:159], 0, s[52:53]
	global_store_dwordx2 v[138:139], v[136:137], off
	v_lshlrev_b32_e32 v136, 16, v132
	v_and_b32_e32 v137, 0xffff0000, v132
	v_lshlrev_b32_e32 v132, 16, v133
	v_and_b32_e32 v133, 0xffff0000, v133
	v_pk_add_f32 v[140:141], v[126:127], v[132:133]
	v_pk_add_f32 v[136:137], v[124:125], v[136:137]
	v_lshlrev_b32_e32 v132, 16, v134
	v_and_b32_e32 v133, 0xffff0000, v134
	v_pk_add_f32 v[160:161], v[128:129], v[132:133]
	v_mul_f32_e32 v132, v137, v137
	v_mul_f32_e32 v133, v141, v141
	v_fmac_f32_e32 v132, v136, v136
	v_fmac_f32_e32 v133, v140, v140
	v_lshlrev_b32_e32 v134, 16, v135
	v_and_b32_e32 v135, 0xffff0000, v135
	v_add_f32_e32 v132, v132, v133
	v_mul_f32_e32 v133, v161, v161
	v_pk_add_f32 v[142:143], v[130:131], v[134:135]
	v_fmac_f32_e32 v133, v160, v160
	v_add_f32_e32 v132, v133, v132
	v_mul_f32_e32 v133, v143, v143
	v_fmac_f32_e32 v133, v142, v142
	v_add_f32_e32 v132, v133, v132
	v_add_f32_e32 v162, v177, v132
	v_cvt_pk_bf16_f32 v132, v136, v137
	v_cvt_pk_bf16_f32 v133, v140, v141
	v_cvt_pk_bf16_f32 v134, v160, v161
	v_cvt_pk_bf16_f32 v135, v142, v143
	global_store_dwordx4 v[158:159], v[132:135], off
	ds_bpermute_b32 v26, v26, v162
	s_waitcnt lgkmcnt(0)
	v_add_f32_e32 v26, v162, v26
	v_mov_b32_e32 v132, v27
	v_mov_b32_e32 v133, v27
	v_cvt_pk_fp8_f32 v132, v136, v137
	v_cvt_pk_fp8_f32 v133, v160, v161
	v_cvt_pk_fp8_f32 v132, v140, v141 op_sel:[0,0,1]
	v_cvt_pk_fp8_f32 v133, v142, v143 op_sel:[0,0,1]
	global_store_dwordx2 v[138:139], v[132:133], off offset:128
	ds_bpermute_b32 v132, v176, v26
	s_and_saveexec_b64 s[52:53], s[0:1]
	s_cbranch_execz .LBB0_756
	s_waitcnt lgkmcnt(0)
	v_add_f32_e32 v26, v26, v132
	v_add_co_u32_e32 v132, vcc, 0x2000, v156
	s_nop 1
	v_addc_co_u32_e32 v133, vcc, 0, v157, vcc
	global_store_dword v[132:133], v26, off offset:3072
